# full barriers: waiting workgroups poll the cross-XCD release generation directly (static per-step target) instead of waiting for their XCD leader's relay; generation compares made monotonic; otherwise
# baseline (speedup 1.0000x reference)
.Lno_early_inv:
	v_cvt_f32_u32_e32 v4, v2
	s_waitcnt vmcnt(0)
	v_readfirstlane_b32 s1, v3
	v_sub_u32_e32 v3, 0, v2
	v_rcp_iflag_f32_e32 v4, v4
	v_add_u32_e32 v5, s1, v1
	v_mul_f32_e32 v4, 0x4f7ffffe, v4
	v_cvt_u32_f32_e32 v4, v4
	v_mul_lo_u32 v1, v3, v4
	v_mul_hi_u32 v1, v4, v1
	v_add_u32_e32 v1, v4, v1
	v_mul_hi_u32 v1, v5, v1
	v_mul_lo_u32 v3, v1, v2
	v_sub_u32_e32 v3, v5, v3
	v_add_u32_e32 v4, 1, v1
	v_cmp_ge_u32_e32 vcc, v3, v2
	s_nop 1
	v_cndmask_b32_e32 v1, v1, v4, vcc
	v_sub_u32_e32 v4, v3, v2
	v_cndmask_b32_e32 v3, v3, v4, vcc
	v_add_u32_e32 v4, 1, v1
	v_cmp_ge_u32_e32 vcc, v3, v2
	v_add_u32_e32 v3, 1, v5
	s_nop 0
	v_cndmask_b32_e32 v1, v1, v4, vcc
	v_mul_lo_u32 v4, v2, v1
	v_add_u32_e32 v2, v4, v2
	v_cmp_ne_u32_e32 vcc, v3, v2
	s_and_saveexec_b64 s[6:7], vcc
	s_xor_b64 s[6:7], exec, s[6:7]
	s_cbranch_execz .LBB0_95
	v_readfirstlane_b32 s1, v15
	s_cmp_lg_u32 s1, 0
	s_cbranch_scc1 .Lnl_xgen
	v_mov_b32_e32 v12, 0x23808
	ds_read_b32 v13, v12
	s_waitcnt lgkmcnt(0)
	v_readfirstlane_b32 s3, v13
	s_cmp_eq_u32 s3, 1
	s_cbranch_scc0 .Lnl_xgen
	s_lshl_b32 s1, 2, s21
	s_add_i32 s1, s1, -1
	s_and_b32 s1, s1, 0x32625252
	s_bcnt1_i32_b32 s1, s1
	v_readlane_b32 s8, v252, 59
	v_readlane_b32 s9, v252, 60
	s_nop 4
.Lnl_tspin:
	global_load_dword v0, v169, s[8:9] sc1
	s_waitcnt vmcnt(0)
	v_cmp_le_u32_e32 vcc, s1, v0
	s_cbranch_vccnz .Lnl_tdone
	s_sleep 1
	s_branch .Lnl_tspin
.Lnl_tdone:
	buffer_inv sc1
	s_waitcnt vmcnt(0)
	s_branch .LBB0_95
